# v40 + gate/up epilogue stores issued two groups late (results stay packed in their registers) so the drain of the next tile's prefetch before the first store no longer stalls
# baseline (speedup 1.0000x reference)
.LBB0_151:
	s_and_b32 s15, s47, 1
	v_lshl_add_u32 v150, s15, 10, v146
	ds_read_b32 v152, v150
	ds_read_b32 v153, v150 offset:64
	ds_read_b32 v154, v150 offset:128
	ds_read_b32 v155, v150 offset:192
	ds_read_b32 v156, v150 offset:512
	ds_read_b32 v157, v150 offset:576
	ds_read_b32 v158, v150 offset:640
	ds_read_b32 v159, v150 offset:704
	v_lshl_or_b32 v140, s23, 7, v144
	v_lshl_add_u32 v149, s22, 8, v142
	v_ashrrev_i32_e32 v141, 31, v140
	s_andn2_b64 vcc, exec, s[2:3]
	v_mov_b64_e32 v[162:163], s[8:9]
	v_lshlrev_b64 v[164:165], 1, v[140:141]
	v_mad_i64_i32 v[160:161], s[22:23], v149, s89, v[162:163]
	s_mov_b32 s100, 0x16000
	s_mov_b32 s101, 0
	s_mov_b32 s98, 0x6e000
	s_mov_b32 s99, 0
	v_lshl_add_u64 v[160:161], v[160:161], 0, v[164:165]
	s_waitcnt lgkmcnt(0)

	v_mul_f32_e32 v122, v122, v152
	v_mul_f32_e32 v126, v126, v152
	v_mul_f32_e32 v123, v123, v152
	v_mul_f32_e32 v127, v127, v152
	v_mul_f32_e32 v124, v124, v152
	v_mul_f32_e32 v128, v128, v152
	v_mul_f32_e32 v125, v125, v152
	v_mul_f32_e32 v129, v129, v152
	v_mul_f32_e32 v114, v114, v152
	v_mul_f32_e32 v118, v118, v152
	v_mul_f32_e32 v115, v115, v152
	v_mul_f32_e32 v119, v119, v152
	v_mul_f32_e32 v116, v116, v152
	v_mul_f32_e32 v120, v120, v152
	v_mul_f32_e32 v117, v117, v152
	v_mul_f32_e32 v121, v121, v152
	v_mul_f32_e32 v166, 0xbfb8aa3b, v126
	v_mul_f32_e32 v167, 0xbfb8aa3b, v127
	v_mul_f32_e32 v168, 0xbfb8aa3b, v128
	v_mul_f32_e32 v169, 0xbfb8aa3b, v129
	v_mul_f32_e32 v170, 0xbfb8aa3b, v118
	v_mul_f32_e32 v171, 0xbfb8aa3b, v119
	v_mul_f32_e32 v172, 0xbfb8aa3b, v120
	v_mul_f32_e32 v173, 0xbfb8aa3b, v121
	v_exp_f32_e32 v166, v166
	v_exp_f32_e32 v167, v167
	v_exp_f32_e32 v168, v168
	v_exp_f32_e32 v169, v169
	v_exp_f32_e32 v170, v170
	v_exp_f32_e32 v171, v171
	v_exp_f32_e32 v172, v172
	v_exp_f32_e32 v173, v173
	v_add_f32_e32 v166, 1.0, v166
	v_add_f32_e32 v167, 1.0, v167
	v_add_f32_e32 v168, 1.0, v168
	v_add_f32_e32 v169, 1.0, v169
	v_add_f32_e32 v170, 1.0, v170
	v_add_f32_e32 v171, 1.0, v171
	v_add_f32_e32 v172, 1.0, v172
	v_add_f32_e32 v173, 1.0, v173
	v_rcp_f32_e32 v166, v166
	v_rcp_f32_e32 v167, v167
	v_rcp_f32_e32 v168, v168
	v_rcp_f32_e32 v169, v169
	v_rcp_f32_e32 v170, v170
	v_rcp_f32_e32 v171, v171
	v_rcp_f32_e32 v172, v172
	v_rcp_f32_e32 v173, v173
	v_mul_f32_e32 v126, v126, v166
	v_mul_f32_e32 v127, v127, v167
	v_mul_f32_e32 v128, v128, v168
	v_mul_f32_e32 v129, v129, v169
	v_mul_f32_e32 v118, v118, v170
	v_mul_f32_e32 v119, v119, v171
	v_mul_f32_e32 v120, v120, v172
	v_mul_f32_e32 v121, v121, v173
	v_mul_f32_e32 v122, v122, v126
	v_mul_f32_e32 v123, v123, v127
	v_mul_f32_e32 v124, v124, v128
	v_mul_f32_e32 v125, v125, v129
	v_mul_f32_e32 v114, v114, v118
	v_mul_f32_e32 v115, v115, v119
	v_mul_f32_e32 v116, v116, v120
	v_mul_f32_e32 v117, v117, v121
	v_cvt_pk_bf16_f32 v126, v122, v123
	v_cvt_pk_bf16_f32 v127, v124, v125
	v_cvt_pk_bf16_f32 v128, v114, v115
	v_cvt_pk_bf16_f32 v129, v116, v117
	s_nop 0
	v_mul_f32_e32 v106, v106, v153
	v_mul_f32_e32 v110, v110, v153
	v_mul_f32_e32 v107, v107, v153
	v_mul_f32_e32 v111, v111, v153
	v_mul_f32_e32 v108, v108, v153
	v_mul_f32_e32 v112, v112, v153
	v_mul_f32_e32 v109, v109, v153
	v_mul_f32_e32 v113, v113, v153
	v_mul_f32_e32 v98, v98, v153
	v_mul_f32_e32 v102, v102, v153
	v_mul_f32_e32 v99, v99, v153
	v_mul_f32_e32 v103, v103, v153
	v_mul_f32_e32 v100, v100, v153
	v_mul_f32_e32 v104, v104, v153
	v_mul_f32_e32 v101, v101, v153
	v_mul_f32_e32 v105, v105, v153
	v_mul_f32_e32 v166, 0xbfb8aa3b, v110
	v_mul_f32_e32 v167, 0xbfb8aa3b, v111
	v_mul_f32_e32 v168, 0xbfb8aa3b, v112
	v_mul_f32_e32 v169, 0xbfb8aa3b, v113
	v_mul_f32_e32 v170, 0xbfb8aa3b, v102
	v_mul_f32_e32 v171, 0xbfb8aa3b, v103
	v_mul_f32_e32 v172, 0xbfb8aa3b, v104
	v_mul_f32_e32 v173, 0xbfb8aa3b, v105
	v_exp_f32_e32 v166, v166
	v_exp_f32_e32 v167, v167
	v_exp_f32_e32 v168, v168
	v_exp_f32_e32 v169, v169
	v_exp_f32_e32 v170, v170
	v_exp_f32_e32 v171, v171
	v_exp_f32_e32 v172, v172
	v_exp_f32_e32 v173, v173
	v_add_f32_e32 v166, 1.0, v166
	v_add_f32_e32 v167, 1.0, v167
	v_add_f32_e32 v168, 1.0, v168
	v_add_f32_e32 v169, 1.0, v169
	v_add_f32_e32 v170, 1.0, v170
	v_add_f32_e32 v171, 1.0, v171
	v_add_f32_e32 v172, 1.0, v172
	v_add_f32_e32 v173, 1.0, v173
	v_rcp_f32_e32 v166, v166
	v_rcp_f32_e32 v167, v167
	v_rcp_f32_e32 v168, v168
	v_rcp_f32_e32 v169, v169
	v_rcp_f32_e32 v170, v170
	v_rcp_f32_e32 v171, v171
	v_rcp_f32_e32 v172, v172
	v_rcp_f32_e32 v173, v173
	v_mul_f32_e32 v110, v110, v166
	v_mul_f32_e32 v111, v111, v167
	v_mul_f32_e32 v112, v112, v168
	v_mul_f32_e32 v113, v113, v169
	v_mul_f32_e32 v102, v102, v170
	v_mul_f32_e32 v103, v103, v171
	v_mul_f32_e32 v104, v104, v172
	v_mul_f32_e32 v105, v105, v173
	v_mul_f32_e32 v106, v106, v110
	v_mul_f32_e32 v107, v107, v111
	v_mul_f32_e32 v108, v108, v112
	v_mul_f32_e32 v109, v109, v113
	v_mul_f32_e32 v98, v98, v102
	v_mul_f32_e32 v99, v99, v103
	v_mul_f32_e32 v100, v100, v104
	v_mul_f32_e32 v101, v101, v105
	v_cvt_pk_bf16_f32 v110, v106, v107
	v_cvt_pk_bf16_f32 v111, v108, v109
	v_cvt_pk_bf16_f32 v112, v98, v99
	v_cvt_pk_bf16_f32 v113, v100, v101
	s_nop 0
	v_mul_f32_e32 v88, v88, v154
	v_mul_f32_e32 v92, v92, v154
	v_mul_f32_e32 v89, v89, v154
	v_mul_f32_e32 v93, v93, v154
	v_mul_f32_e32 v90, v90, v154
	v_mul_f32_e32 v94, v94, v154
	v_mul_f32_e32 v91, v91, v154
	v_mul_f32_e32 v95, v95, v154
	v_mul_f32_e32 v80, v80, v154
	v_mul_f32_e32 v84, v84, v154
	v_mul_f32_e32 v81, v81, v154
	v_mul_f32_e32 v85, v85, v154
	v_mul_f32_e32 v82, v82, v154
	v_mul_f32_e32 v86, v86, v154
	v_mul_f32_e32 v83, v83, v154
	v_mul_f32_e32 v87, v87, v154
	v_mul_f32_e32 v166, 0xbfb8aa3b, v92
	v_mul_f32_e32 v167, 0xbfb8aa3b, v93
	v_mul_f32_e32 v168, 0xbfb8aa3b, v94
	v_mul_f32_e32 v169, 0xbfb8aa3b, v95
	v_mul_f32_e32 v170, 0xbfb8aa3b, v84
	v_mul_f32_e32 v171, 0xbfb8aa3b, v85
	v_mul_f32_e32 v172, 0xbfb8aa3b, v86
	v_mul_f32_e32 v173, 0xbfb8aa3b, v87
	v_exp_f32_e32 v166, v166
	v_exp_f32_e32 v167, v167
	v_exp_f32_e32 v168, v168
	v_exp_f32_e32 v169, v169
	v_exp_f32_e32 v170, v170
	v_exp_f32_e32 v171, v171
	v_exp_f32_e32 v172, v172
	v_exp_f32_e32 v173, v173
	v_add_f32_e32 v166, 1.0, v166
	v_add_f32_e32 v167, 1.0, v167
	v_add_f32_e32 v168, 1.0, v168
	v_add_f32_e32 v169, 1.0, v169
	v_add_f32_e32 v170, 1.0, v170
	v_add_f32_e32 v171, 1.0, v171
	v_add_f32_e32 v172, 1.0, v172
	v_add_f32_e32 v173, 1.0, v173
	v_rcp_f32_e32 v166, v166
	v_rcp_f32_e32 v167, v167
	v_rcp_f32_e32 v168, v168
	v_rcp_f32_e32 v169, v169
	v_rcp_f32_e32 v170, v170
	v_rcp_f32_e32 v171, v171
	v_rcp_f32_e32 v172, v172
	v_rcp_f32_e32 v173, v173
	v_mul_f32_e32 v92, v92, v166
	v_mul_f32_e32 v93, v93, v167
	v_mul_f32_e32 v94, v94, v168
	v_mul_f32_e32 v95, v95, v169
	v_mul_f32_e32 v84, v84, v170
	v_mul_f32_e32 v85, v85, v171
	v_mul_f32_e32 v86, v86, v172
	v_mul_f32_e32 v87, v87, v173
	v_mul_f32_e32 v88, v88, v92
	v_mul_f32_e32 v89, v89, v93
	v_mul_f32_e32 v90, v90, v94
	v_mul_f32_e32 v91, v91, v95
	v_mul_f32_e32 v80, v80, v84
	v_mul_f32_e32 v81, v81, v85
	v_mul_f32_e32 v82, v82, v86
	v_mul_f32_e32 v83, v83, v87
	v_cvt_pk_bf16_f32 v92, v88, v89
	v_cvt_pk_bf16_f32 v93, v90, v91
	v_cvt_pk_bf16_f32 v94, v80, v81
	v_cvt_pk_bf16_f32 v95, v82, v83
	s_nop 0
	s_waitcnt vmcnt(0)
	global_store_dwordx4 v[160:161], v[126:129], off sc1
	v_lshl_add_u64 v[160:161], s[100:101], 0, v[160:161]
	v_mul_f32_e32 v72, v72, v155
	v_mul_f32_e32 v76, v76, v155
	v_mul_f32_e32 v73, v73, v155
	v_mul_f32_e32 v77, v77, v155
	v_mul_f32_e32 v74, v74, v155
	v_mul_f32_e32 v78, v78, v155
	v_mul_f32_e32 v75, v75, v155
	v_mul_f32_e32 v79, v79, v155
	v_mul_f32_e32 v64, v64, v155
	v_mul_f32_e32 v68, v68, v155
	v_mul_f32_e32 v65, v65, v155
	v_mul_f32_e32 v69, v69, v155
	v_mul_f32_e32 v66, v66, v155
	v_mul_f32_e32 v70, v70, v155
	v_mul_f32_e32 v67, v67, v155
	v_mul_f32_e32 v71, v71, v155
	v_mul_f32_e32 v166, 0xbfb8aa3b, v76
	v_mul_f32_e32 v167, 0xbfb8aa3b, v77
	v_mul_f32_e32 v168, 0xbfb8aa3b, v78
	v_mul_f32_e32 v169, 0xbfb8aa3b, v79
	v_mul_f32_e32 v170, 0xbfb8aa3b, v68
	v_mul_f32_e32 v171, 0xbfb8aa3b, v69
	v_mul_f32_e32 v172, 0xbfb8aa3b, v70
	v_mul_f32_e32 v173, 0xbfb8aa3b, v71
	v_exp_f32_e32 v166, v166
	v_exp_f32_e32 v167, v167
	v_exp_f32_e32 v168, v168
	v_exp_f32_e32 v169, v169
	v_exp_f32_e32 v170, v170
	v_exp_f32_e32 v171, v171
	v_exp_f32_e32 v172, v172
	v_exp_f32_e32 v173, v173
	v_add_f32_e32 v166, 1.0, v166
	v_add_f32_e32 v167, 1.0, v167
	v_add_f32_e32 v168, 1.0, v168
	v_add_f32_e32 v169, 1.0, v169
	v_add_f32_e32 v170, 1.0, v170
	v_add_f32_e32 v171, 1.0, v171
	v_add_f32_e32 v172, 1.0, v172
	v_add_f32_e32 v173, 1.0, v173
	v_rcp_f32_e32 v166, v166
	v_rcp_f32_e32 v167, v167
	v_rcp_f32_e32 v168, v168
	v_rcp_f32_e32 v169, v169
	v_rcp_f32_e32 v170, v170
	v_rcp_f32_e32 v171, v171
	v_rcp_f32_e32 v172, v172
	v_rcp_f32_e32 v173, v173
	v_mul_f32_e32 v76, v76, v166
	v_mul_f32_e32 v77, v77, v167
	v_mul_f32_e32 v78, v78, v168
	v_mul_f32_e32 v79, v79, v169
	v_mul_f32_e32 v68, v68, v170
	v_mul_f32_e32 v69, v69, v171
	v_mul_f32_e32 v70, v70, v172
	v_mul_f32_e32 v71, v71, v173
	v_mul_f32_e32 v72, v72, v76
	v_mul_f32_e32 v73, v73, v77
	v_mul_f32_e32 v74, v74, v78
	v_mul_f32_e32 v75, v75, v79
	v_mul_f32_e32 v64, v64, v68
	v_mul_f32_e32 v65, v65, v69
	v_mul_f32_e32 v66, v66, v70
	v_mul_f32_e32 v67, v67, v71
	v_cvt_pk_bf16_f32 v76, v72, v73
	v_cvt_pk_bf16_f32 v77, v74, v75
	v_cvt_pk_bf16_f32 v78, v64, v65
	v_cvt_pk_bf16_f32 v79, v66, v67
	s_nop 0
	global_store_dwordx4 v[160:161], v[110:113], off sc1
	v_lshl_add_u64 v[160:161], s[100:101], 0, v[160:161]
	v_mul_f32_e32 v56, v56, v156
	v_mul_f32_e32 v60, v60, v156
	v_mul_f32_e32 v57, v57, v156
	v_mul_f32_e32 v61, v61, v156
	v_mul_f32_e32 v58, v58, v156
	v_mul_f32_e32 v62, v62, v156
	v_mul_f32_e32 v59, v59, v156
	v_mul_f32_e32 v63, v63, v156
	v_mul_f32_e32 v48, v48, v156
	v_mul_f32_e32 v52, v52, v156
	v_mul_f32_e32 v49, v49, v156
	v_mul_f32_e32 v53, v53, v156
	v_mul_f32_e32 v50, v50, v156
	v_mul_f32_e32 v54, v54, v156
	v_mul_f32_e32 v51, v51, v156
	v_mul_f32_e32 v55, v55, v156
	v_mul_f32_e32 v166, 0xbfb8aa3b, v60
	v_mul_f32_e32 v167, 0xbfb8aa3b, v61
	v_mul_f32_e32 v168, 0xbfb8aa3b, v62
	v_mul_f32_e32 v169, 0xbfb8aa3b, v63
	v_mul_f32_e32 v170, 0xbfb8aa3b, v52
	v_mul_f32_e32 v171, 0xbfb8aa3b, v53
	v_mul_f32_e32 v172, 0xbfb8aa3b, v54
	v_mul_f32_e32 v173, 0xbfb8aa3b, v55
	v_exp_f32_e32 v166, v166
	v_exp_f32_e32 v167, v167
	v_exp_f32_e32 v168, v168
	v_exp_f32_e32 v169, v169
	v_exp_f32_e32 v170, v170
	v_exp_f32_e32 v171, v171
	v_exp_f32_e32 v172, v172
	v_exp_f32_e32 v173, v173
	v_add_f32_e32 v166, 1.0, v166
	v_add_f32_e32 v167, 1.0, v167
	v_add_f32_e32 v168, 1.0, v168
	v_add_f32_e32 v169, 1.0, v169
	v_add_f32_e32 v170, 1.0, v170
	v_add_f32_e32 v171, 1.0, v171
	v_add_f32_e32 v172, 1.0, v172
	v_add_f32_e32 v173, 1.0, v173
	v_rcp_f32_e32 v166, v166
	v_rcp_f32_e32 v167, v167
	v_rcp_f32_e32 v168, v168
	v_rcp_f32_e32 v169, v169
	v_rcp_f32_e32 v170, v170
	v_rcp_f32_e32 v171, v171
	v_rcp_f32_e32 v172, v172
	v_rcp_f32_e32 v173, v173
	v_mul_f32_e32 v60, v60, v166
	v_mul_f32_e32 v61, v61, v167
	v_mul_f32_e32 v62, v62, v168
	v_mul_f32_e32 v63, v63, v169
	v_mul_f32_e32 v52, v52, v170
	v_mul_f32_e32 v53, v53, v171
	v_mul_f32_e32 v54, v54, v172
	v_mul_f32_e32 v55, v55, v173
	v_mul_f32_e32 v56, v56, v60
	v_mul_f32_e32 v57, v57, v61
	v_mul_f32_e32 v58, v58, v62
	v_mul_f32_e32 v59, v59, v63
	v_mul_f32_e32 v48, v48, v52
	v_mul_f32_e32 v49, v49, v53
	v_mul_f32_e32 v50, v50, v54
	v_mul_f32_e32 v51, v51, v55
	v_cvt_pk_bf16_f32 v60, v56, v57
	v_cvt_pk_bf16_f32 v61, v58, v59
	v_cvt_pk_bf16_f32 v62, v48, v49
	v_cvt_pk_bf16_f32 v63, v50, v51
	s_nop 0
	global_store_dwordx4 v[160:161], v[92:95], off sc1
	v_lshl_add_u64 v[160:161], s[100:101], 0, v[160:161]
	v_mul_f32_e32 v40, v40, v157
	v_mul_f32_e32 v44, v44, v157
	v_mul_f32_e32 v41, v41, v157
	v_mul_f32_e32 v45, v45, v157
	v_mul_f32_e32 v42, v42, v157
	v_mul_f32_e32 v46, v46, v157
	v_mul_f32_e32 v43, v43, v157
	v_mul_f32_e32 v47, v47, v157
	v_mul_f32_e32 v32, v32, v157
	v_mul_f32_e32 v36, v36, v157
	v_mul_f32_e32 v33, v33, v157
	v_mul_f32_e32 v37, v37, v157
	v_mul_f32_e32 v34, v34, v157
	v_mul_f32_e32 v38, v38, v157
	v_mul_f32_e32 v35, v35, v157
	v_mul_f32_e32 v39, v39, v157
	v_mul_f32_e32 v166, 0xbfb8aa3b, v44
	v_mul_f32_e32 v167, 0xbfb8aa3b, v45
	v_mul_f32_e32 v168, 0xbfb8aa3b, v46
	v_mul_f32_e32 v169, 0xbfb8aa3b, v47
	v_mul_f32_e32 v170, 0xbfb8aa3b, v36
	v_mul_f32_e32 v171, 0xbfb8aa3b, v37
	v_mul_f32_e32 v172, 0xbfb8aa3b, v38
	v_mul_f32_e32 v173, 0xbfb8aa3b, v39
	v_exp_f32_e32 v166, v166
	v_exp_f32_e32 v167, v167
	v_exp_f32_e32 v168, v168
	v_exp_f32_e32 v169, v169
	v_exp_f32_e32 v170, v170
	v_exp_f32_e32 v171, v171
	v_exp_f32_e32 v172, v172
	v_exp_f32_e32 v173, v173
	v_add_f32_e32 v166, 1.0, v166
	v_add_f32_e32 v167, 1.0, v167
	v_add_f32_e32 v168, 1.0, v168
	v_add_f32_e32 v169, 1.0, v169
	v_add_f32_e32 v170, 1.0, v170
	v_add_f32_e32 v171, 1.0, v171
	v_add_f32_e32 v172, 1.0, v172
	v_add_f32_e32 v173, 1.0, v173
	v_rcp_f32_e32 v166, v166
	v_rcp_f32_e32 v167, v167
	v_rcp_f32_e32 v168, v168
	v_rcp_f32_e32 v169, v169
	v_rcp_f32_e32 v170, v170
	v_rcp_f32_e32 v171, v171
	v_rcp_f32_e32 v172, v172
	v_rcp_f32_e32 v173, v173
	v_mul_f32_e32 v44, v44, v166
	v_mul_f32_e32 v45, v45, v167
	v_mul_f32_e32 v46, v46, v168
	v_mul_f32_e32 v47, v47, v169
	v_mul_f32_e32 v36, v36, v170
	v_mul_f32_e32 v37, v37, v171
	v_mul_f32_e32 v38, v38, v172
	v_mul_f32_e32 v39, v39, v173
	v_mul_f32_e32 v40, v40, v44
	v_mul_f32_e32 v41, v41, v45
	v_mul_f32_e32 v42, v42, v46
	v_mul_f32_e32 v43, v43, v47
	v_mul_f32_e32 v32, v32, v36
	v_mul_f32_e32 v33, v33, v37
	v_mul_f32_e32 v34, v34, v38
	v_mul_f32_e32 v35, v35, v39
	v_cvt_pk_bf16_f32 v44, v40, v41
	v_cvt_pk_bf16_f32 v45, v42, v43
	v_cvt_pk_bf16_f32 v46, v32, v33
	v_cvt_pk_bf16_f32 v47, v34, v35
	s_nop 0
	global_store_dwordx4 v[160:161], v[76:79], off sc1
	v_lshl_add_u64 v[160:161], s[98:99], 0, v[160:161]
	v_mul_f32_e32 v24, v24, v158
	v_mul_f32_e32 v28, v28, v158
	v_mul_f32_e32 v25, v25, v158
	v_mul_f32_e32 v29, v29, v158
	v_mul_f32_e32 v26, v26, v158
	v_mul_f32_e32 v30, v30, v158
	v_mul_f32_e32 v27, v27, v158
	v_mul_f32_e32 v31, v31, v158
	v_mul_f32_e32 v16, v16, v158
	v_mul_f32_e32 v20, v20, v158
	v_mul_f32_e32 v17, v17, v158
	v_mul_f32_e32 v21, v21, v158
	v_mul_f32_e32 v18, v18, v158
	v_mul_f32_e32 v22, v22, v158
	v_mul_f32_e32 v19, v19, v158
	v_mul_f32_e32 v23, v23, v158
	v_mul_f32_e32 v166, 0xbfb8aa3b, v28
	v_mul_f32_e32 v167, 0xbfb8aa3b, v29
	v_mul_f32_e32 v168, 0xbfb8aa3b, v30
	v_mul_f32_e32 v169, 0xbfb8aa3b, v31
	v_mul_f32_e32 v170, 0xbfb8aa3b, v20
	v_mul_f32_e32 v171, 0xbfb8aa3b, v21
	v_mul_f32_e32 v172, 0xbfb8aa3b, v22
	v_mul_f32_e32 v173, 0xbfb8aa3b, v23
	v_exp_f32_e32 v166, v166
	v_exp_f32_e32 v167, v167
	v_exp_f32_e32 v168, v168
	v_exp_f32_e32 v169, v169
	v_exp_f32_e32 v170, v170
	v_exp_f32_e32 v171, v171
	v_exp_f32_e32 v172, v172
	v_exp_f32_e32 v173, v173
	v_add_f32_e32 v166, 1.0, v166
	v_add_f32_e32 v167, 1.0, v167
	v_add_f32_e32 v168, 1.0, v168
	v_add_f32_e32 v169, 1.0, v169
	v_add_f32_e32 v170, 1.0, v170
	v_add_f32_e32 v171, 1.0, v171
	v_add_f32_e32 v172, 1.0, v172
	v_add_f32_e32 v173, 1.0, v173
	v_rcp_f32_e32 v166, v166
	v_rcp_f32_e32 v167, v167
	v_rcp_f32_e32 v168, v168
	v_rcp_f32_e32 v169, v169
	v_rcp_f32_e32 v170, v170
	v_rcp_f32_e32 v171, v171
	v_rcp_f32_e32 v172, v172
	v_rcp_f32_e32 v173, v173
	v_mul_f32_e32 v28, v28, v166
	v_mul_f32_e32 v29, v29, v167
	v_mul_f32_e32 v30, v30, v168
	v_mul_f32_e32 v31, v31, v169
	v_mul_f32_e32 v20, v20, v170
	v_mul_f32_e32 v21, v21, v171
	v_mul_f32_e32 v22, v22, v172
	v_mul_f32_e32 v23, v23, v173
	v_mul_f32_e32 v24, v24, v28
	v_mul_f32_e32 v25, v25, v29
	v_mul_f32_e32 v26, v26, v30
	v_mul_f32_e32 v27, v27, v31
	v_mul_f32_e32 v16, v16, v20
	v_mul_f32_e32 v17, v17, v21
	v_mul_f32_e32 v18, v18, v22
	v_mul_f32_e32 v19, v19, v23
	v_cvt_pk_bf16_f32 v28, v24, v25
	v_cvt_pk_bf16_f32 v29, v26, v27
	v_cvt_pk_bf16_f32 v30, v16, v17
	v_cvt_pk_bf16_f32 v31, v18, v19
	s_nop 0
	global_store_dwordx4 v[160:161], v[60:63], off sc1
	v_lshl_add_u64 v[160:161], s[100:101], 0, v[160:161]
	v_mul_f32_e32 v8, v8, v159
	v_mul_f32_e32 v12, v12, v159
	v_mul_f32_e32 v9, v9, v159
	v_mul_f32_e32 v13, v13, v159
	v_mul_f32_e32 v10, v10, v159
	v_mul_f32_e32 v14, v14, v159
	v_mul_f32_e32 v11, v11, v159
	v_mul_f32_e32 v15, v15, v159
	v_mul_f32_e32 v0, v0, v159
	v_mul_f32_e32 v4, v4, v159
	v_mul_f32_e32 v1, v1, v159
	v_mul_f32_e32 v5, v5, v159
	v_mul_f32_e32 v2, v2, v159
	v_mul_f32_e32 v6, v6, v159
	v_mul_f32_e32 v3, v3, v159
	v_mul_f32_e32 v7, v7, v159
	v_mul_f32_e32 v166, 0xbfb8aa3b, v12
	v_mul_f32_e32 v167, 0xbfb8aa3b, v13
	v_mul_f32_e32 v168, 0xbfb8aa3b, v14
	v_mul_f32_e32 v169, 0xbfb8aa3b, v15
	v_mul_f32_e32 v170, 0xbfb8aa3b, v4
	v_mul_f32_e32 v171, 0xbfb8aa3b, v5
	v_mul_f32_e32 v172, 0xbfb8aa3b, v6
	v_mul_f32_e32 v173, 0xbfb8aa3b, v7
	v_exp_f32_e32 v166, v166
	v_exp_f32_e32 v167, v167
	v_exp_f32_e32 v168, v168
	v_exp_f32_e32 v169, v169
	v_exp_f32_e32 v170, v170
	v_exp_f32_e32 v171, v171
	v_exp_f32_e32 v172, v172
	v_exp_f32_e32 v173, v173
	v_add_f32_e32 v166, 1.0, v166
	v_add_f32_e32 v167, 1.0, v167
	v_add_f32_e32 v168, 1.0, v168
	v_add_f32_e32 v169, 1.0, v169
	v_add_f32_e32 v170, 1.0, v170
	v_add_f32_e32 v171, 1.0, v171
	v_add_f32_e32 v172, 1.0, v172
	v_add_f32_e32 v173, 1.0, v173
	v_rcp_f32_e32 v166, v166
	v_rcp_f32_e32 v167, v167
	v_rcp_f32_e32 v168, v168
	v_rcp_f32_e32 v169, v169
	v_rcp_f32_e32 v170, v170
	v_rcp_f32_e32 v171, v171
	v_rcp_f32_e32 v172, v172
	v_rcp_f32_e32 v173, v173
	v_mul_f32_e32 v12, v12, v166
	v_mul_f32_e32 v13, v13, v167
	v_mul_f32_e32 v14, v14, v168
	v_mul_f32_e32 v15, v15, v169
	v_mul_f32_e32 v4, v4, v170
	v_mul_f32_e32 v5, v5, v171
	v_mul_f32_e32 v6, v6, v172
	v_mul_f32_e32 v7, v7, v173
	v_mul_f32_e32 v8, v8, v12
	v_mul_f32_e32 v9, v9, v13
	v_mul_f32_e32 v10, v10, v14
	v_mul_f32_e32 v11, v11, v15
	v_mul_f32_e32 v0, v0, v4
	v_mul_f32_e32 v1, v1, v5
	v_mul_f32_e32 v2, v2, v6
	v_mul_f32_e32 v3, v3, v7
	v_cvt_pk_bf16_f32 v12, v8, v9
	v_cvt_pk_bf16_f32 v13, v10, v11
	v_cvt_pk_bf16_f32 v14, v0, v1
	v_cvt_pk_bf16_f32 v15, v2, v3
	s_nop 0
	global_store_dwordx4 v[160:161], v[44:47], off sc1
	v_lshl_add_u64 v[160:161], s[100:101], 0, v[160:161]
	global_store_dwordx4 v[160:161], v[28:31], off sc1
	v_lshl_add_u64 v[160:161], s[100:101], 0, v[160:161]
	global_store_dwordx4 v[160:161], v[12:15], off sc1
	s_nop 1
	s_mov_b64 s[22:23], -1
	s_cbranch_vccnz .LBB0_142
	s_andn2_b64 vcc, exec, s[6:7]
	s_cbranch_vccnz .LBB0_141
	s_barrier
	s_branch .LBB0_141
